# EpiSwiGLU: the 8 per-block rs LDS reads issued once at the epilogue top (one wait) instead of read+wait per block
# baseline (speedup 1.0000x reference)
;     __device__ __forceinline__ void operator()(const Acc& acc, const Unit& u, int wr, int wc, int fr, int fq, const RsCtx& rc) const {
;     ...
;             for (int m = 0; m < 4; ++m) { const int row = EPI_ROW(u, ai, wr, m, fr); const float rs = rc.get(u.pm, ai * 128 + wr * 64 + m * 16 + fr, row);
.LBB0_147:
	s_mov_b32 s100, 0
	s_cmp_eq_u32 s48, s3
	s_cbranch_scc1 .Lswg_pre
	s_cmp_lg_u32 s48, s12
	s_cbranch_scc1 .Lswg_nopre
	s_movk_i32 s100, 0x400
.Lswg_pre:
	v_add_u32_e32 v165, s100, v147
	ds_read_b32 v158, v165
	ds_read_b32 v159, v165 offset:64
	ds_read_b32 v160, v165 offset:128
	ds_read_b32 v161, v165 offset:192
	ds_read_b32 v162, v165 offset:512
	ds_read_b32 v163, v165 offset:576
	ds_read_b32 v164, v165 offset:640
	ds_read_b32 v165, v165 offset:704

;     __device__ __forceinline__ void operator()(const Acc& acc, const Unit& u, int wr, int wc, int fr, int fq, const RsCtx& rc) const {
;     ...
;             for (int m = 0; m < 4; ++m) { const int row = EPI_ROW(u, ai, wr, m, fr); const float rs = rc.get(u.pm, ai * 128 + wr * 64 + m * 16 + fr, row);
.LBB0_150:
	s_andn2_b64 vcc, exec, s[6:7]
	s_cbranch_vccnz .LBB0_152
	s_waitcnt lgkmcnt(0)
	v_mov_b32_e32 v144, v158

;     __device__ __forceinline__ void operator()(const Acc& acc, const Unit& u, int wr, int wc, int fr, int fq, const RsCtx& rc) const {
;     ...
;             for (int m = 0; m < 4; ++m) { const int row = EPI_ROW(u, ai, wr, m, fr); const float rs = rc.get(u.pm, ai * 128 + wr * 64 + m * 16 + fr, row);
.LBB0_153:
	s_andn2_b64 vcc, exec, s[6:7]
	s_cbranch_vccnz .LBB0_155
	s_waitcnt lgkmcnt(0)
	s_waitcnt lgkmcnt(0)
	v_mov_b32_e32 v144, v158

;     __device__ __forceinline__ void operator()(const Acc& acc, const Unit& u, int wr, int wc, int fr, int fq, const RsCtx& rc) const {
;     ...
;             for (int m = 0; m < 4; ++m) { const int row = EPI_ROW(u, ai, wr, m, fr); const float rs = rc.get(u.pm, ai * 128 + wr * 64 + m * 16 + fr, row);
.LBB0_158:
	s_andn2_b64 vcc, exec, s[24:25]
	s_cbranch_vccnz .LBB0_160
	s_waitcnt lgkmcnt(0)
	v_mov_b32_e32 v116, v159

;     __device__ __forceinline__ void operator()(const Acc& acc, const Unit& u, int wr, int wc, int fr, int fq, const RsCtx& rc) const {
;     ...
;             for (int m = 0; m < 4; ++m) { const int row = EPI_ROW(u, ai, wr, m, fr); const float rs = rc.get(u.pm, ai * 128 + wr * 64 + m * 16 + fr, row);
.LBB0_161:
	s_andn2_b64 vcc, exec, s[28:29]
	s_cbranch_vccnz .LBB0_163
	s_waitcnt lgkmcnt(0)
	s_waitcnt lgkmcnt(0)
	v_mov_b32_e32 v116, v159

;     __device__ __forceinline__ void operator()(const Acc& acc, const Unit& u, int wr, int wc, int fr, int fq, const RsCtx& rc) const {
;     ...
;             for (int m = 0; m < 4; ++m) { const int row = EPI_ROW(u, ai, wr, m, fr); const float rs = rc.get(u.pm, ai * 128 + wr * 64 + m * 16 + fr, row);
.LBB0_166:
	s_andn2_b64 vcc, exec, s[24:25]
	s_cbranch_vccnz .LBB0_168
	s_waitcnt lgkmcnt(0)
	v_mov_b32_e32 v100, v160

;     __device__ __forceinline__ void operator()(const Acc& acc, const Unit& u, int wr, int wc, int fr, int fq, const RsCtx& rc) const {
;     ...
;             for (int m = 0; m < 4; ++m) { const int row = EPI_ROW(u, ai, wr, m, fr); const float rs = rc.get(u.pm, ai * 128 + wr * 64 + m * 16 + fr, row);
.LBB0_169:
	s_andn2_b64 vcc, exec, s[24:25]
	s_cbranch_vccnz .LBB0_171
	s_waitcnt lgkmcnt(0)
	s_waitcnt lgkmcnt(0)
	v_mov_b32_e32 v100, v160

;     __device__ __forceinline__ void operator()(const Acc& acc, const Unit& u, int wr, int wc, int fr, int fq, const RsCtx& rc) const {
;     ...
;             for (int m = 0; m < 4; ++m) { const int row = EPI_ROW(u, ai, wr, m, fr); const float rs = rc.get(u.pm, ai * 128 + wr * 64 + m * 16 + fr, row);
.LBB0_174:
	s_andn2_b64 vcc, exec, s[24:25]
	s_cbranch_vccnz .LBB0_176
	s_waitcnt lgkmcnt(0)
	v_mov_b32_e32 v84, v161

;     __device__ __forceinline__ void operator()(const Acc& acc, const Unit& u, int wr, int wc, int fr, int fq, const RsCtx& rc) const {
;     ...
;             for (int m = 0; m < 4; ++m) { const int row = EPI_ROW(u, ai, wr, m, fr); const float rs = rc.get(u.pm, ai * 128 + wr * 64 + m * 16 + fr, row);
.LBB0_177:
	s_andn2_b64 vcc, exec, s[24:25]
	s_cbranch_vccnz .LBB0_179
	s_waitcnt lgkmcnt(0)
	s_waitcnt lgkmcnt(0)
	v_mov_b32_e32 v84, v161

;     __device__ __forceinline__ void operator()(const Acc& acc, const Unit& u, int wr, int wc, int fr, int fq, const RsCtx& rc) const {
;     ...
;             for (int m = 0; m < 4; ++m) { const int row = EPI_ROW(u, ai, wr, m, fr); const float rs = rc.get(u.pm, ai * 128 + wr * 64 + m * 16 + fr, row);
.LBB0_182:
	s_andn2_b64 vcc, exec, s[24:25]
	s_cbranch_vccnz .LBB0_184
	s_waitcnt lgkmcnt(0)
	v_mov_b32_e32 v68, v162

;     __device__ __forceinline__ void operator()(const Acc& acc, const Unit& u, int wr, int wc, int fr, int fq, const RsCtx& rc) const {
;     ...
;             for (int m = 0; m < 4; ++m) { const int row = EPI_ROW(u, ai, wr, m, fr); const float rs = rc.get(u.pm, ai * 128 + wr * 64 + m * 16 + fr, row);
.LBB0_185:
	s_andn2_b64 vcc, exec, s[24:25]
	s_cbranch_vccnz .LBB0_187
	s_waitcnt lgkmcnt(0)
	s_waitcnt lgkmcnt(0)
	v_mov_b32_e32 v68, v162

;     __device__ __forceinline__ void operator()(const Acc& acc, const Unit& u, int wr, int wc, int fr, int fq, const RsCtx& rc) const {
;     ...
;             for (int m = 0; m < 4; ++m) { const int row = EPI_ROW(u, ai, wr, m, fr); const float rs = rc.get(u.pm, ai * 128 + wr * 64 + m * 16 + fr, row);
.LBB0_190:
	s_andn2_b64 vcc, exec, s[24:25]
	s_cbranch_vccnz .LBB0_192
	s_waitcnt lgkmcnt(0)
	v_mov_b32_e32 v52, v163

;     __device__ __forceinline__ void operator()(const Acc& acc, const Unit& u, int wr, int wc, int fr, int fq, const RsCtx& rc) const {
;     ...
;             for (int m = 0; m < 4; ++m) { const int row = EPI_ROW(u, ai, wr, m, fr); const float rs = rc.get(u.pm, ai * 128 + wr * 64 + m * 16 + fr, row);
.LBB0_193:
	s_andn2_b64 vcc, exec, s[24:25]
	s_cbranch_vccnz .LBB0_195
	s_waitcnt lgkmcnt(0)
	s_waitcnt lgkmcnt(0)
	v_mov_b32_e32 v52, v163

;     __device__ __forceinline__ void operator()(const Acc& acc, const Unit& u, int wr, int wc, int fr, int fq, const RsCtx& rc) const {
;     ...
;             for (int m = 0; m < 4; ++m) { const int row = EPI_ROW(u, ai, wr, m, fr); const float rs = rc.get(u.pm, ai * 128 + wr * 64 + m * 16 + fr, row);
.LBB0_198:
	s_andn2_b64 vcc, exec, s[24:25]
	s_cbranch_vccnz .LBB0_200
	s_waitcnt lgkmcnt(0)
	v_mov_b32_e32 v36, v164

;     __device__ __forceinline__ void operator()(const Acc& acc, const Unit& u, int wr, int wc, int fr, int fq, const RsCtx& rc) const {
;     ...
;             for (int m = 0; m < 4; ++m) { const int row = EPI_ROW(u, ai, wr, m, fr); const float rs = rc.get(u.pm, ai * 128 + wr * 64 + m * 16 + fr, row);
.LBB0_201:
	s_andn2_b64 vcc, exec, s[24:25]
	s_cbranch_vccnz .LBB0_203
	s_waitcnt lgkmcnt(0)
	s_waitcnt lgkmcnt(0)
	v_mov_b32_e32 v36, v164

;     __device__ __forceinline__ void operator()(const Acc& acc, const Unit& u, int wr, int wc, int fr, int fq, const RsCtx& rc) const {
;     ...
;             for (int m = 0; m < 4; ++m) { const int row = EPI_ROW(u, ai, wr, m, fr); const float rs = rc.get(u.pm, ai * 128 + wr * 64 + m * 16 + fr, row);
.LBB0_206:
	s_andn2_b64 vcc, exec, s[6:7]
	s_cbranch_vccnz .LBB0_208
	s_waitcnt lgkmcnt(0)
	v_mov_b32_e32 v20, v165

;     __device__ __forceinline__ void operator()(const Acc& acc, const Unit& u, int wr, int wc, int fr, int fq, const RsCtx& rc) const {
;     ...
;             for (int m = 0; m < 4; ++m) { const int row = EPI_ROW(u, ai, wr, m, fr); const float rs = rc.get(u.pm, ai * 128 + wr * 64 + m * 16 + fr, row);
.LBB0_209:
	s_andn2_b64 vcc, exec, s[24:25]
	s_cbranch_vccnz .LBB0_211
	s_waitcnt lgkmcnt(0)
	s_waitcnt lgkmcnt(0)
	v_mov_b32_e32 v20, v165
